# v22 + P5 epilogue L2 prefetch extended to the next tile's second K-tile (one more 128-byte line per row)
# baseline (speedup 1.0000x reference)
.LBB0_164:
	v_mov_b32 v198, v0
	s_lshl_b32 s33, s42, 7
	v_and_b32_e32 v202, 15, v198
	v_lshlrev_b32_e32 v197, 3, v202
	v_or_b32_e32 v194, s33, v197
	v_ashrrev_i32_e32 v195, 31, v194
	v_lshlrev_b64 v[42:43], 2, v[194:195]
	v_readlane_b32 s0, v254, 19
	v_lshl_add_u64 v[6:7], s[86:87], 0, v[42:43]
	v_readlane_b32 s1, v254, 20
	global_load_dwordx4 v[2:5], v[6:7], off offset:16
	global_load_dwordx4 v[18:21], v[6:7], off
	v_lshl_add_u64 v[6:7], s[0:1], 0, v[42:43]
	v_readlane_b32 s0, v254, 21
	v_readlane_b32 s1, v254, 22
	global_load_dwordx4 v[58:61], v[6:7], off offset:16
	global_load_dwordx4 v[62:65], v[6:7], off
	v_lshl_add_u64 v[10:11], s[0:1], 0, v[42:43]
	v_readlane_b32 s0, v254, 23
	v_readlane_b32 s1, v254, 24
	global_load_dwordx4 v[6:9], v[10:11], off offset:16
	global_load_dwordx4 v[22:25], v[10:11], off
	v_lshl_add_u64 v[10:11], s[0:1], 0, v[42:43]
	v_readlane_b32 s0, v254, 25
	v_readlane_b32 s1, v254, 26
	global_load_dwordx4 v[46:49], v[10:11], off offset:16
	global_load_dwordx4 v[34:37], v[10:11], off
	v_lshl_add_u64 v[14:15], s[0:1], 0, v[42:43]
	v_readlane_b32 s0, v254, 27
	v_readlane_b32 s1, v254, 28
	global_load_dwordx4 v[10:13], v[14:15], off offset:16
	global_load_dwordx4 v[26:29], v[14:15], off
	v_lshl_add_u64 v[14:15], s[0:1], 0, v[42:43]
	v_readlane_b32 s0, v254, 29
	v_readlane_b32 s1, v254, 30
	v_lshl_add_u64 v[30:31], s[88:89], 0, v[42:43]
	global_load_dwordx4 v[50:53], v[14:15], off offset:16
	global_load_dwordx4 v[38:41], v[14:15], off
	v_lshl_add_u64 v[42:43], s[0:1], 0, v[42:43]
	global_load_dwordx4 v[14:17], v[30:31], off offset:16
	s_nop 0
	global_load_dwordx4 v[30:33], v[30:31], off
	s_nop 0
	global_load_dwordx4 v[54:57], v[42:43], off offset:16
	s_nop 0
	global_load_dwordx4 v[42:45], v[42:43], off
	v_lshrrev_b32_e32 v199, 2, v198
	s_mov_b32 s0, 0xfffffc0
	v_and_or_b32 v199, v199, s0, v202
	s_movk_i32 s0, 0x210
	v_mul_lo_u32 v199, v199, s0
	v_cvt_pk_bf16_f32 v182, v182, v183
	v_cvt_pk_bf16_f32 v183, v184, v185
	v_lshrrev_b32_e32 v184, 1, v198
	v_add_u32_e32 v199, 0, v199
	v_and_b32_e32 v184, 24, v184
	v_and_b32_e32 v185, 0xc0, v198
	v_add3_u32 v184, v199, v185, v184
	v_cvt_pk_bf16_f32 v122, v122, v123
	v_cvt_pk_bf16_f32 v123, v124, v125
	v_cvt_pk_bf16_f32 v114, v114, v115
	v_cvt_pk_bf16_f32 v115, v116, v117
	v_add_u32_e32 v124, 0x6000, v184
	v_cvt_pk_bf16_f32 v116, v130, v131
	ds_write2_b64 v124, v[122:123], v[114:115] offset0:96 offset1:100
	v_cvt_pk_bf16_f32 v114, v138, v139
	v_cvt_pk_bf16_f32 v115, v140, v141
	v_cvt_pk_bf16_f32 v117, v132, v133
	ds_write2_b64 v124, v[114:115], v[116:117] offset0:128 offset1:132
	v_add_u32_e32 v116, 0x10800, v184
	v_cvt_pk_bf16_f32 v86, v86, v87
	v_cvt_pk_bf16_f32 v87, v88, v89
	v_add_u32_e32 v88, 0x14a20, v184
	v_cvt_pk_bf16_f32 v114, v142, v143
	v_cvt_pk_bf16_f32 v115, v144, v145
	ds_write_b64 v116, v[114:115]
	v_add_u32_e32 v116, 0x10820, v184
	ds_write_b64 v88, v[86:87]
	v_cvt_pk_bf16_f32 v86, v90, v91
	v_add_u32_e32 v88, 0x14b00, v184
	v_cvt_pk_bf16_f32 v114, v126, v127
	v_cvt_pk_bf16_f32 v115, v128, v129
	ds_write_b64 v116, v[114:115]
	v_add_u32_e32 v116, 0x10900, v184
	v_cvt_pk_bf16_f32 v102, v102, v103
	v_cvt_pk_bf16_f32 v103, v104, v105
	v_add_u32_e32 v104, 0x12920, v184
	v_cvt_pk_bf16_f32 v87, v92, v93
	ds_write_b64 v88, v[86:87]
	v_cvt_pk_bf16_f32 v78, v78, v79
	v_cvt_pk_bf16_f32 v79, v80, v81
	v_add_u32_e32 v80, 0x16b00, v184
	v_cvt_pk_bf16_f32 v70, v70, v71
	v_cvt_pk_bf16_f32 v71, v72, v73
	v_add_u32_e32 v72, 0x16b20, v184
	v_cvt_pk_bf16_f32 v66, v66, v67
	v_cvt_pk_bf16_f32 v67, v68, v69
	v_add_u32_e32 v68, 0x16c20, v184
	v_ashrrev_i32_e32 v86, 4, v198
	s_movk_i32 s16, 0x1080
	v_cvt_pk_bf16_f32 v178, v178, v179
	v_cvt_pk_bf16_f32 v179, v180, v181
	v_cvt_pk_bf16_f32 v166, v166, v167
	v_cvt_pk_bf16_f32 v167, v168, v169
	v_cvt_pk_bf16_f32 v162, v162, v163
	v_cvt_pk_bf16_f32 v163, v164, v165
	v_add_u32_e32 v168, 0x2000, v184
	v_cvt_pk_bf16_f32 v150, v150, v151
	v_cvt_pk_bf16_f32 v151, v152, v153
	v_cvt_pk_bf16_f32 v146, v146, v147
	v_cvt_pk_bf16_f32 v147, v148, v149
	v_add_u32_e32 v152, 0x4000, v184
	v_cvt_pk_bf16_f32 v114, v134, v135
	v_cvt_pk_bf16_f32 v115, v136, v137
	ds_write_b64 v116, v[114:115]
	v_add_u32_e32 v116, 0x10920, v184
	v_cvt_pk_bf16_f32 v110, v110, v111
	v_cvt_pk_bf16_f32 v111, v112, v113
	v_add_u32_e32 v112, 0x12900, v184
	ds_write_b64 v104, v[102:103]
	v_add_u32_e32 v104, 0x12a00, v184
	v_cvt_pk_bf16_f32 v98, v98, v99
	v_cvt_pk_bf16_f32 v99, v100, v101
	v_add_u32_e32 v100, 0x12a20, v184
	v_cvt_pk_bf16_f32 v94, v94, v95
	v_cvt_pk_bf16_f32 v95, v96, v97
	v_add_u32_e32 v96, 0x14a00, v184
	v_cvt_pk_bf16_f32 v82, v82, v83
	v_cvt_pk_bf16_f32 v83, v84, v85
	v_add_u32_e32 v84, 0x14b20, v184
	ds_write_b64 v80, v[78:79]
	ds_write_b64 v72, v[70:71]
	v_add_u32_e32 v72, 0x16c00, v184
	ds_write_b64 v68, v[66:67]
	v_cmp_lt_i32_e32 vcc, 0, v86
	v_cmp_gt_i32_e64 s[0:1], 1, v86
	v_lshlrev_b32_e32 v80, 4, v202
	v_mul_lo_u32 v66, v86, s16
	ds_write2_b64 v184, v[182:183], v[178:179] offset1:4
	v_cvt_pk_bf16_f32 v178, v190, v191
	v_cvt_pk_bf16_f32 v179, v192, v193
	v_cvt_pk_bf16_f32 v180, v186, v187
	v_cvt_pk_bf16_f32 v181, v188, v189
	ds_write2_b64 v184, v[178:179], v[180:181] offset0:32 offset1:36
	ds_write2_b64 v168, v[166:167], v[162:163] offset0:32 offset1:36
	v_cvt_pk_bf16_f32 v162, v174, v175
	v_cvt_pk_bf16_f32 v163, v176, v177
	v_cvt_pk_bf16_f32 v164, v170, v171
	v_cvt_pk_bf16_f32 v165, v172, v173
	ds_write2_b64 v168, v[162:163], v[164:165] offset0:64 offset1:68
	ds_write2_b64 v152, v[150:151], v[146:147] offset0:64 offset1:68
	v_cvt_pk_bf16_f32 v146, v158, v159
	v_cvt_pk_bf16_f32 v147, v160, v161
	v_cvt_pk_bf16_f32 v148, v154, v155
	v_cvt_pk_bf16_f32 v149, v156, v157
	ds_write2_b64 v152, v[146:147], v[148:149] offset0:96 offset1:100
	v_cvt_pk_bf16_f32 v114, v118, v119
	v_cvt_pk_bf16_f32 v115, v120, v121
	ds_write_b64 v116, v[114:115]
	ds_write_b64 v112, v[110:111]
	v_cvt_pk_bf16_f32 v102, v106, v107
	v_cvt_pk_bf16_f32 v103, v108, v109
	ds_write_b64 v104, v[102:103]
	ds_write_b64 v100, v[98:99]
	ds_write_b64 v96, v[94:95]
	ds_write_b64 v84, v[82:83]
	v_cvt_pk_bf16_f32 v70, v74, v75
	v_cvt_pk_bf16_f32 v71, v76, v77
	ds_write_b64 v72, v[70:71]
	s_waitcnt vmcnt(0) lgkmcnt(0)
	s_barrier
	s_add_i32 s52, s42, 4
	s_cmp_lt_i32 s52, 22
	s_cbranch_scc0 .Lp5_pf_skip
	v_readlane_b32 s54, v255, 33
	v_readlane_b32 s55, v255, 34
	v_readlane_b32 s56, v255, 35
	v_readlane_b32 s57, v255, 36
	s_lshl_b32 s53, s36, 19
	s_add_u32 s54, s54, s53
	s_addc_u32 s55, s55, 0
	s_lshl_b32 s53, s52, 19
	s_add_u32 s56, s56, s53
	s_addc_u32 s57, s57, 0
	v_readfirstlane_b32 s53, v0
	s_nop 1
	s_cmp_lt_u32 s53, 0x100
	s_cselect_b32 s54, s54, s56
	s_cselect_b32 s55, s55, s57
	v_and_b32_e32 v222, 0xff, v0
	v_lshlrev_b32_e32 v222, 11, v222
	global_load_dword v250, v222, s[54:55]
	global_load_dword v250, v222, s[54:55] offset:128
